# in-projection q|k|v epilogue: the four QK-norm gain loads issued together with one wait (were four load+vmcnt(0) round trips)
# baseline (speedup 1.0000x reference)
;     __device__ __forceinline__ void operator()(f32x4 (&acc)[2][2][4][2], const Unit& u, int wr, int wc, int fr, int fq) const {
;     ...
;             if (lc0 < 512) { gp = qkn_swa; sc = QC2; } else if (lc0 < 640) { gp = qkn_swa + 64; } else if (lc0 < 768) { } else if (lc0 < 1280) { gp = qkn_diff; sc = QC2; } else if (lc0 < 1792) { gp = qkn_diff + 64; }
;             f32x4 gv[2][2];
; #pragma unroll
;             for (int bj = 0; bj < 2; ++bj)
; #pragma unroll
;                 for (int n = 0; n < 2; ++n) gv[bj][n] = gp ? *(const f32x4*)(gp + 32 * bj + 8 * fq + 4 * n) * sc : (f32x4){1.f, 1.f, 1.f, 1.f};
.LBB0_148:
	s_cmp_eq_u64 s[42:43], 0
	s_cselect_b64 s[40:41], -1, 0
	s_cmp_lg_u64 s[42:43], 0
	v_lshlrev_b32_e32 v0, 2, v170
	s_cselect_b64 s[76:77], -1, 0
	s_mov_b32 s69, s68
	v_lshl_add_u64 v[192:193], s[42:43], 0, v[0:1]
	v_mov_b32_e32 v146, 1.0
	s_and_b64 vcc, exec, s[40:41]
	v_mov_b32_e32 v148, 1.0
	v_mov_b32_e32 v149, 1.0
	v_mov_b32_e32 v150, 1.0
	v_mov_b32_e32 v151, 1.0
	s_cbranch_vccnz .LBB0_150
.LBB0_150:
	v_cndmask_b32_e64 v0, 0, 1, s[76:77]
	v_cmp_ne_u32_e64 s[42:43], 1, v0
	s_andn2_b64 vcc, exec, s[76:77]
	v_mov_b32_e32 v147, 1.0
	v_mov_b32_e32 v152, 1.0
	v_mov_b32_e32 v153, 1.0
	s_cbranch_vccnz .LBB0_152
.LBB0_152:
	v_mov_b32_e32 v154, 1.0
	s_and_b64 vcc, exec, s[42:43]
	v_mov_b32_e32 v156, 1.0
	v_mov_b32_e32 v157, 1.0
	v_mov_b32_e32 v158, 1.0
	v_mov_b32_e32 v159, 1.0
	s_cbranch_vccnz .LBB0_154
.LBB0_154:
	s_and_b64 vcc, exec, s[42:43]
	v_mov_b32_e32 v155, 1.0
	v_mov_b32_e32 v160, 1.0
	v_mov_b32_e32 v161, 1.0
	s_cbranch_vccnz .LBB0_156
	global_load_dwordx4 v[224:227], v[192:193], off
	global_load_dwordx4 v[228:231], v[192:193], off offset:16
	global_load_dwordx4 v[232:235], v[192:193], off offset:128
	global_load_dwordx4 v[236:239], v[192:193], off offset:144
	s_mov_b32 s48, s68
	s_mov_b32 s49, s68
	s_waitcnt vmcnt(0)
	v_pk_mul_f32 v[150:151], s[48:49], v[226:227]
	v_pk_mul_f32 v[148:149], s[48:49], v[224:225]
	v_pk_mul_f32 v[152:153], s[48:49], v[230:231]
	v_pk_mul_f32 v[146:147], s[48:49], v[228:229]
	v_pk_mul_f32 v[158:159], s[48:49], v[234:235]
	v_pk_mul_f32 v[156:157], s[48:49], v[232:233]
	v_pk_mul_f32 v[160:161], s[48:49], v[238:239]
	v_pk_mul_f32 v[154:155], s[48:49], v[236:237]
